# MLA softmax row-max: ds_bpermute LDS round trips replaced by v_permlane16/32_swap (4 per tile per wave)
# speedup vs baseline: 1.0126x; 1.0126x over previous
.LBB0_1385:
	s_cmp_gt_i32 s21, s17
	s_cbranch_scc1 .LBB0_1391
	s_bitcmp1_b32 s21, 0
	s_cselect_b32 s19, 0xa000, 0
	s_add_i32 s19, s19, 0
	ds_read_b128 v[104:107], v232
	ds_read_b128 v[108:111], v232 offset:1024
	ds_read_b128 v[112:115], v232 offset:2048
	ds_read_b128 v[116:119], v232 offset:3072
	v_add_u32_e32 v120, s19, v165
	v_add_u32_e32 v237, s19, v223
	v_add_u32_e32 v156, v120, v227
	v_add_u32_e32 v158, v120, v229
	v_add_u32_e32 v235, v237, v222
	v_add_u32_e32 v242, s19, v224
	v_add_u32_e32 v157, v120, v228
	ds_read_b128 v[96:99], v156
	ds_read_b128 v[100:103], v157
	v_add_u32_e32 v159, v120, v230
	ds_read_b128 v[120:123], v158
	ds_read_b128 v[124:127], v159
	v_add_u32_e32 v236, v242, v222
	ds_read_b128 v[128:131], v235 offset:16384
	ds_read_b128 v[132:135], v236 offset:16384
	s_setprio 1
	v_xor_b32_e32 v136, 0x80000000, v234
	v_xor_b32_e32 v140, 0x80000000, v233
	v_mov_b32_e32 v137, v136
	v_mov_b32_e32 v138, v136
	v_mov_b32_e32 v139, v136
	v_mov_b32_e32 v141, v140
	v_mov_b32_e32 v142, v140
	v_mov_b32_e32 v143, v140
	s_waitcnt lgkmcnt(0)
	v_mfma_f32_16x16x32_bf16 v[144:147], v[96:99], v[40:43], v[136:139]
	v_mfma_f32_16x16x32_bf16 v[96:99], v[96:99], v[56:59], v[140:143]
	v_mfma_f32_16x16x32_bf16 v[144:147], v[100:103], v[44:47], v[144:147]
	v_mfma_f32_16x16x32_bf16 v[96:99], v[100:103], v[60:63], v[96:99]
	v_mfma_f32_16x16x32_bf16 v[100:103], v[120:123], v[48:51], v[144:147]
	v_mfma_f32_16x16x32_bf16 v[96:99], v[120:123], v[64:67], v[96:99]
	v_mfma_f32_16x16x32_bf16 v[100:103], v[124:127], v[52:55], v[100:103]
	v_mfma_f32_16x16x32_bf16 v[96:99], v[124:127], v[68:71], v[96:99]
	v_mfma_f32_16x16x32_bf16 v[100:103], v[128:131], v[104:107], v[100:103]
	v_mfma_f32_16x16x32_bf16 v[96:99], v[128:131], v[112:115], v[96:99]
	v_mfma_f32_16x16x32_bf16 v[144:147], v[132:135], v[108:111], v[100:103]
	v_mfma_f32_16x16x32_bf16 v[96:99], v[132:135], v[116:119], v[96:99]
	s_setprio 0
	s_nop 3
	ds_read_b128 v[100:103], v156 offset:4096
	ds_read_b128 v[120:123], v157 offset:4096
	ds_read_b128 v[124:127], v158 offset:4096
	ds_read_b128 v[128:131], v159 offset:4096
	ds_read_b128 v[132:135], v235 offset:18432
	ds_read_b128 v[152:155], v236 offset:18432
	s_setprio 1
	s_waitcnt lgkmcnt(0)
	v_mfma_f32_16x16x32_bf16 v[148:151], v[100:103], v[40:43], v[136:139]
	v_mfma_f32_16x16x32_bf16 v[100:103], v[100:103], v[56:59], v[140:143]
	v_mfma_f32_16x16x32_bf16 v[148:151], v[120:123], v[44:47], v[148:151]
	v_mfma_f32_16x16x32_bf16 v[100:103], v[120:123], v[60:63], v[100:103]
	v_mfma_f32_16x16x32_bf16 v[120:123], v[124:127], v[48:51], v[148:151]
	v_mfma_f32_16x16x32_bf16 v[100:103], v[124:127], v[64:67], v[100:103]
	v_mfma_f32_16x16x32_bf16 v[120:123], v[128:131], v[52:55], v[120:123]
	v_mfma_f32_16x16x32_bf16 v[100:103], v[128:131], v[68:71], v[100:103]
	v_mfma_f32_16x16x32_bf16 v[120:123], v[132:135], v[104:107], v[120:123]
	v_mfma_f32_16x16x32_bf16 v[100:103], v[132:135], v[112:115], v[100:103]
	v_mfma_f32_16x16x32_bf16 v[148:151], v[152:155], v[108:111], v[120:123]
	v_mfma_f32_16x16x32_bf16 v[100:103], v[152:155], v[116:119], v[100:103]
	s_setprio 0
	s_nop 3
	ds_read_b128 v[120:123], v156 offset:8192
	ds_read_b128 v[124:127], v157 offset:8192
	ds_read_b128 v[128:131], v158 offset:8192
	ds_read_b128 v[132:135], v159 offset:8192
	ds_read_b128 v[152:155], v235 offset:20480
	ds_read_b128 v[156:159], v236 offset:20480
	s_setprio 1
	s_waitcnt lgkmcnt(0)
	v_mfma_f32_16x16x32_bf16 v[238:241], v[120:123], v[40:43], v[136:139]
	v_mfma_f32_16x16x32_bf16 v[120:123], v[120:123], v[56:59], v[140:143]
	v_mfma_f32_16x16x32_bf16 v[238:241], v[124:127], v[44:47], v[238:241]
	v_mfma_f32_16x16x32_bf16 v[120:123], v[124:127], v[60:63], v[120:123]
	v_mfma_f32_16x16x32_bf16 v[124:127], v[128:131], v[48:51], v[238:241]
	v_mfma_f32_16x16x32_bf16 v[120:123], v[128:131], v[64:67], v[120:123]
	v_mfma_f32_16x16x32_bf16 v[124:127], v[132:135], v[52:55], v[124:127]
	v_mfma_f32_16x16x32_bf16 v[120:123], v[132:135], v[68:71], v[120:123]
	v_mfma_f32_16x16x32_bf16 v[124:127], v[152:155], v[104:107], v[124:127]
	v_mfma_f32_16x16x32_bf16 v[120:123], v[152:155], v[112:115], v[120:123]
	v_mfma_f32_16x16x32_bf16 v[152:155], v[156:159], v[108:111], v[124:127]
	v_mfma_f32_16x16x32_bf16 v[128:131], v[156:159], v[116:119], v[120:123]
	s_setprio 0
	v_add_u32_e32 v132, s19, v225
	s_nop 3
	v_add_u32_e32 v120, v132, v227
	v_add_u32_e32 v124, v132, v228
	v_add_u32_e32 v133, v132, v229
	v_add_u32_e32 v156, v132, v230
	v_add_u32_e32 v237, v237, v226
	v_add_u32_e32 v242, v242, v226
	ds_read_b128 v[120:123], v120
	ds_read_b128 v[124:127], v124
	ds_read_b128 v[132:135], v133
	ds_read_b128 v[156:159], v156
	ds_read_b128 v[238:241], v237 offset:16384
	ds_read_b128 v[242:245], v242 offset:16384
	s_setprio 1
	s_waitcnt lgkmcnt(0)
	v_mfma_f32_16x16x32_bf16 v[136:139], v[120:123], v[40:43], v[136:139]
	v_mfma_f32_16x16x32_bf16 v[120:123], v[120:123], v[56:59], v[140:143]
	v_mfma_f32_16x16x32_bf16 v[136:139], v[124:127], v[44:47], v[136:139]
	v_mfma_f32_16x16x32_bf16 v[120:123], v[124:127], v[60:63], v[120:123]
	v_mfma_f32_16x16x32_bf16 v[124:127], v[132:135], v[48:51], v[136:139]
	v_mfma_f32_16x16x32_bf16 v[120:123], v[132:135], v[64:67], v[120:123]
	v_mfma_f32_16x16x32_bf16 v[124:127], v[156:159], v[52:55], v[124:127]
	v_mfma_f32_16x16x32_bf16 v[120:123], v[156:159], v[68:71], v[120:123]
	v_mfma_f32_16x16x32_bf16 v[104:107], v[238:241], v[104:107], v[124:127]
	v_mfma_f32_16x16x32_bf16 v[112:115], v[238:241], v[112:115], v[120:123]
	v_mfma_f32_16x16x32_bf16 v[156:159], v[242:245], v[108:111], v[104:107]
	v_mfma_f32_16x16x32_bf16 v[140:143], v[242:245], v[116:119], v[112:115]
	s_setprio 0
	s_nop 2
	ds_read_b128 v[120:123], v235 offset:24576
	ds_read_b128 v[124:127], v235 offset:26624
	ds_read_b128 v[108:111], v236 offset:24576
	ds_read_b128 v[104:107], v236 offset:26624
	ds_read_b128 v[132:135], v235 offset:28672
	ds_read_b128 v[136:139], v235 offset:30720
	ds_read_b128 v[116:119], v236 offset:28672
	ds_read_b128 v[112:115], v236 offset:30720
	v_max3_f32 v239, v144, s27, v145
	v_max3_f32 v239, v239, v146, v147
	v_max3_f32 v239, v239, v148, v149
	v_max3_f32 v239, v239, v150, v151
	v_max3_f32 v239, v239, v152, v153
	v_max3_f32 v239, v239, v154, v155
	v_max3_f32 v239, v239, v156, v157
	v_max3_f32 v239, v239, v158, v159
	s_cmp_eq_u32 s21, 0
	s_cselect_b64 s[38:39], -1, 0
	v_mov_b32_e32 v240, v239
	s_nop 1
	v_permlane16_swap_b32_e32 v240, v239
	v_max_f32_e32 v239, v239, v240
	v_mov_b32_e32 v240, v239
	s_nop 1
	v_permlane32_swap_b32_e32 v240, v239
	v_max_f32_e32 v239, v239, v240
	v_cmp_lt_f32_e32 vcc, s7, v239
	s_or_b64 vcc, s[38:39], vcc
	s_cbranch_vccz .LBB0_1388
	v_max_f32_e32 v240, v239, v239
	v_max_f32_e32 v240, 0, v240
	v_cndmask_b32_e64 v239, v240, v239, s[38:39]
	v_exp_f32_e64 v240, -v239
	v_add_f32_e32 v234, v234, v239
	v_sub_f32_e32 v144, v144, v239
	v_sub_f32_e32 v145, v145, v239
	v_mul_f32_e32 v195, v195, v240
	v_sub_f32_e32 v146, v146, v239
	v_sub_f32_e32 v147, v147, v239
	v_sub_f32_e32 v148, v148, v239
	v_sub_f32_e32 v149, v149, v239
	v_sub_f32_e32 v150, v150, v239
	v_sub_f32_e32 v151, v151, v239
	v_sub_f32_e32 v152, v152, v239
	v_sub_f32_e32 v153, v153, v239
	v_sub_f32_e32 v154, v154, v239
	v_sub_f32_e32 v155, v155, v239
	v_sub_f32_e32 v156, v156, v239
	v_sub_f32_e32 v157, v157, v239
	v_sub_f32_e32 v158, v158, v239
	v_sub_f32_e32 v159, v159, v239
	v_pk_mul_f32 v[94:95], v[94:95], v[240:241] op_sel_hi:[1,0]
	v_pk_mul_f32 v[92:93], v[92:93], v[240:241] op_sel_hi:[1,0]
	v_pk_mul_f32 v[90:91], v[90:91], v[240:241] op_sel_hi:[1,0]
	v_pk_mul_f32 v[88:89], v[88:89], v[240:241] op_sel_hi:[1,0]
	v_pk_mul_f32 v[86:87], v[86:87], v[240:241] op_sel_hi:[1,0]
	v_pk_mul_f32 v[84:85], v[84:85], v[240:241] op_sel_hi:[1,0]
	v_pk_mul_f32 v[82:83], v[82:83], v[240:241] op_sel_hi:[1,0]
	v_pk_mul_f32 v[80:81], v[80:81], v[240:241] op_sel_hi:[1,0]
	v_pk_mul_f32 v[78:79], v[78:79], v[240:241] op_sel_hi:[1,0]
	v_pk_mul_f32 v[76:77], v[76:77], v[240:241] op_sel_hi:[1,0]
	v_pk_mul_f32 v[74:75], v[74:75], v[240:241] op_sel_hi:[1,0]
	v_pk_mul_f32 v[72:73], v[72:73], v[240:241] op_sel_hi:[1,0]
	v_pk_mul_f32 v[38:39], v[38:39], v[240:241] op_sel_hi:[1,0]
	v_pk_mul_f32 v[36:37], v[36:37], v[240:241] op_sel_hi:[1,0]
	v_pk_mul_f32 v[34:35], v[34:35], v[240:241] op_sel_hi:[1,0]
	v_pk_mul_f32 v[32:33], v[32:33], v[240:241] op_sel_hi:[1,0]
.LBB0_1388:
	v_max3_f32 v239, v96, s27, v97
	v_max3_f32 v239, v239, v98, v99
	v_max3_f32 v239, v239, v100, v101
	v_max3_f32 v239, v239, v102, v103
	v_max3_f32 v239, v239, v128, v129
	v_max3_f32 v239, v239, v130, v131
	v_max3_f32 v239, v239, v140, v141
	v_max3_f32 v239, v239, v142, v143
	v_mov_b32_e32 v237, v239
	s_nop 1
	v_permlane16_swap_b32_e32 v237, v239
	v_max_f32_e32 v237, v239, v237
	v_mov_b32_e32 v238, v237
	s_nop 1
	v_permlane32_swap_b32_e32 v238, v237
	v_max_f32_e32 v237, v237, v238
	v_cmp_lt_f32_e32 vcc, s7, v237
	s_or_b64 s[28:29], s[38:39], vcc
	v_cndmask_b32_e64 v238, 0, 1, s[28:29]
	v_cmp_ne_u32_e32 vcc, 0, v238
	s_cbranch_vccz .LBB0_1390
	v_max_f32_e32 v238, v237, v237
	v_max_f32_e32 v238, 0, v238
	v_cndmask_b32_e64 v237, v238, v237, s[38:39]
	v_exp_f32_e64 v238, -v237
	v_add_f32_e32 v233, v233, v237
	v_sub_f32_e32 v96, v96, v237
	v_sub_f32_e32 v97, v97, v237
	v_mul_f32_e32 v193, v193, v238
	v_sub_f32_e32 v98, v98, v237
	v_sub_f32_e32 v99, v99, v237
	v_sub_f32_e32 v100, v100, v237
	v_sub_f32_e32 v101, v101, v237
	v_sub_f32_e32 v102, v102, v237
	v_sub_f32_e32 v103, v103, v237
	v_sub_f32_e32 v128, v128, v237
	v_sub_f32_e32 v129, v129, v237
	v_sub_f32_e32 v130, v130, v237
	v_sub_f32_e32 v131, v131, v237
	v_sub_f32_e32 v140, v140, v237
	v_sub_f32_e32 v141, v141, v237
	v_sub_f32_e32 v142, v142, v237
	v_sub_f32_e32 v143, v143, v237
	v_pk_mul_f32 v[30:31], v[30:31], v[238:239] op_sel_hi:[1,0]
	v_pk_mul_f32 v[28:29], v[28:29], v[238:239] op_sel_hi:[1,0]
	v_pk_mul_f32 v[26:27], v[26:27], v[238:239] op_sel_hi:[1,0]
	v_pk_mul_f32 v[24:25], v[24:25], v[238:239] op_sel_hi:[1,0]
	v_pk_mul_f32 v[22:23], v[22:23], v[238:239] op_sel_hi:[1,0]
	v_pk_mul_f32 v[20:21], v[20:21], v[238:239] op_sel_hi:[1,0]
	v_pk_mul_f32 v[18:19], v[18:19], v[238:239] op_sel_hi:[1,0]
	v_pk_mul_f32 v[16:17], v[16:17], v[238:239] op_sel_hi:[1,0]
	v_pk_mul_f32 v[14:15], v[14:15], v[238:239] op_sel_hi:[1,0]
	v_pk_mul_f32 v[12:13], v[12:13], v[238:239] op_sel_hi:[1,0]
	v_pk_mul_f32 v[10:11], v[10:11], v[238:239] op_sel_hi:[1,0]
	v_pk_mul_f32 v[8:9], v[8:9], v[238:239] op_sel_hi:[1,0]
	v_pk_mul_f32 v[6:7], v[6:7], v[238:239] op_sel_hi:[1,0]
	v_pk_mul_f32 v[4:5], v[4:5], v[238:239] op_sel_hi:[1,0]
	v_pk_mul_f32 v[2:3], v[2:3], v[238:239] op_sel_hi:[1,0]
	v_pk_mul_f32 v[0:1], v[0:1], v[238:239] op_sel_hi:[1,0]
.LBB0_1390:
	v_exp_f32_e32 v144, v144
	v_exp_f32_e32 v145, v145
	v_exp_f32_e32 v146, v146
	v_exp_f32_e32 v147, v147
	v_add_f32_e32 v237, 0, v144
	v_exp_f32_e32 v148, v148
	v_add_f32_e32 v237, v237, v145
	v_exp_f32_e32 v149, v149
	v_add_f32_e32 v237, v146, v237
	v_exp_f32_e32 v150, v150
	v_add_f32_e32 v237, v147, v237
	v_exp_f32_e32 v151, v151
	v_add_f32_e32 v237, v148, v237
	v_exp_f32_e32 v152, v152
	v_exp_f32_e32 v153, v153
	v_exp_f32_e32 v96, v96
	v_add_f32_e32 v237, v149, v237
	v_exp_f32_e32 v97, v97
	v_add_f32_e32 v237, v150, v237
	v_exp_f32_e32 v98, v98
	v_add_f32_e32 v237, v151, v237
	v_exp_f32_e32 v99, v99
	v_add_f32_e32 v237, v152, v237
	v_cvt_pk_bf16_f32 v144, v144, v145
	v_cvt_pk_bf16_f32 v145, v146, v147
	v_cvt_pk_bf16_f32 v146, v148, v149
	v_cvt_pk_bf16_f32 v148, v152, v153
	v_add_f32_e32 v152, 0, v96
	v_exp_f32_e32 v100, v100
	v_add_f32_e32 v152, v152, v97
	v_exp_f32_e32 v101, v101
	v_add_f32_e32 v152, v98, v152
	v_exp_f32_e32 v102, v102
	v_add_f32_e32 v152, v99, v152
	v_exp_f32_e32 v103, v103
	v_add_f32_e32 v152, v100, v152
	v_exp_f32_e32 v128, v128
	v_add_f32_e32 v152, v101, v152
	v_exp_f32_e32 v129, v129
	v_exp_f32_e32 v154, v154
	v_add_f32_e32 v152, v102, v152
	v_exp_f32_e32 v130, v130
	v_exp_f32_e32 v155, v155
	v_add_f32_e32 v152, v103, v152
	v_exp_f32_e32 v131, v131
	v_exp_f32_e32 v156, v156
	v_add_f32_e32 v152, v128, v152
	v_exp_f32_e32 v140, v140
	v_add_f32_e32 v237, v153, v237
	v_exp_f32_e32 v157, v157
	v_add_f32_e32 v152, v129, v152
	v_exp_f32_e32 v141, v141
	v_add_f32_e32 v237, v154, v237
	v_exp_f32_e32 v158, v158
	v_add_f32_e32 v152, v130, v152
	v_exp_f32_e32 v142, v142
	v_add_f32_e32 v237, v155, v237
	v_exp_f32_e32 v159, v159
	v_add_f32_e32 v152, v131, v152
	v_exp_f32_e32 v143, v143
	v_add_f32_e32 v237, v156, v237
	v_add_f32_e32 v152, v140, v152
	v_add_f32_e32 v237, v157, v237
	v_add_f32_e32 v152, v141, v152
	v_add_f32_e32 v237, v158, v237
	v_add_f32_e32 v152, v142, v152
	v_add_f32_e32 v237, v159, v237
	v_add_f32_e32 v152, v143, v152
	v_add_f32_e32 v195, v195, v237
	v_add_f32_e32 v193, v193, v152
	v_cvt_pk_bf16_f32 v147, v150, v151
	v_cvt_pk_bf16_f32 v149, v154, v155
	v_cvt_pk_bf16_f32 v150, v156, v157
	v_cvt_pk_bf16_f32 v151, v158, v159
	v_cvt_pk_bf16_f32 v96, v96, v97
	v_cvt_pk_bf16_f32 v97, v98, v99
	v_cvt_pk_bf16_f32 v98, v100, v101
	v_cvt_pk_bf16_f32 v99, v102, v103
	v_cvt_pk_bf16_f32 v100, v128, v129
	v_cvt_pk_bf16_f32 v101, v130, v131
	v_cvt_pk_bf16_f32 v102, v140, v141
	v_cvt_pk_bf16_f32 v103, v142, v143
	s_waitcnt lgkmcnt(0)
	s_setprio 1
	v_mfma_f32_16x16x32_bf16 v[92:95], v[120:123], v[144:147], v[92:95]
	v_mfma_f32_16x16x32_bf16 v[28:31], v[120:123], v[96:99], v[28:31]
	v_mfma_f32_16x16x32_bf16 v[88:91], v[124:127], v[144:147], v[88:91]
	v_mfma_f32_16x16x32_bf16 v[24:27], v[124:127], v[96:99], v[24:27]
	v_mfma_f32_16x16x32_bf16 v[84:87], v[132:135], v[144:147], v[84:87]
	v_mfma_f32_16x16x32_bf16 v[20:23], v[132:135], v[96:99], v[20:23]
	v_mfma_f32_16x16x32_bf16 v[80:83], v[136:139], v[144:147], v[80:83]
	v_mfma_f32_16x16x32_bf16 v[16:19], v[136:139], v[96:99], v[16:19]
	v_mfma_f32_16x16x32_bf16 v[92:95], v[108:111], v[148:151], v[92:95]
	v_mfma_f32_16x16x32_bf16 v[28:31], v[108:111], v[100:103], v[28:31]
	v_mfma_f32_16x16x32_bf16 v[88:91], v[104:107], v[148:151], v[88:91]
	v_mfma_f32_16x16x32_bf16 v[24:27], v[104:107], v[100:103], v[24:27]
	v_mfma_f32_16x16x32_bf16 v[84:87], v[116:119], v[148:151], v[84:87]
	v_mfma_f32_16x16x32_bf16 v[20:23], v[116:119], v[100:103], v[20:23]
	v_mfma_f32_16x16x32_bf16 v[80:83], v[112:115], v[148:151], v[80:83]
	v_mfma_f32_16x16x32_bf16 v[16:19], v[112:115], v[100:103], v[16:19]
	s_setprio 0
	ds_read_b128 v[104:107], v235 offset:32768
	ds_read_b128 v[108:111], v235 offset:34816
	ds_read_b128 v[112:115], v236 offset:32768
	ds_read_b128 v[116:119], v236 offset:34816
	ds_read_b128 v[120:123], v235 offset:36864
	ds_read_b128 v[124:127], v235 offset:38912
	ds_read_b128 v[128:131], v236 offset:36864
	ds_read_b128 v[132:135], v236 offset:38912
	s_setprio 1
	s_waitcnt lgkmcnt(0)
	v_mfma_f32_16x16x32_bf16 v[76:79], v[104:107], v[144:147], v[76:79]
	v_mfma_f32_16x16x32_bf16 v[12:15], v[104:107], v[96:99], v[12:15]
	v_mfma_f32_16x16x32_bf16 v[72:75], v[108:111], v[144:147], v[72:75]
	v_mfma_f32_16x16x32_bf16 v[8:11], v[108:111], v[96:99], v[8:11]
	v_mfma_f32_16x16x32_bf16 v[36:39], v[120:123], v[144:147], v[36:39]
	v_mfma_f32_16x16x32_bf16 v[4:7], v[120:123], v[96:99], v[4:7]
	v_mfma_f32_16x16x32_bf16 v[32:35], v[124:127], v[144:147], v[32:35]
	v_mfma_f32_16x16x32_bf16 v[0:3], v[124:127], v[96:99], v[0:3]
	v_mfma_f32_16x16x32_bf16 v[76:79], v[112:115], v[148:151], v[76:79]
	v_mfma_f32_16x16x32_bf16 v[12:15], v[112:115], v[100:103], v[12:15]
	v_mfma_f32_16x16x32_bf16 v[72:75], v[116:119], v[148:151], v[72:75]
	v_mfma_f32_16x16x32_bf16 v[8:11], v[116:119], v[100:103], v[8:11]
	v_mfma_f32_16x16x32_bf16 v[36:39], v[128:131], v[148:151], v[36:39]
	v_mfma_f32_16x16x32_bf16 v[4:7], v[128:131], v[100:103], v[4:7]
	v_mfma_f32_16x16x32_bf16 v[32:35], v[132:135], v[148:151], v[32:35]
	v_mfma_f32_16x16x32_bf16 v[0:3], v[132:135], v[100:103], v[0:3]
	s_setprio 0
